# phase C: per-row sum-of-squares loads issued in one batch (was one 16-byte load per trip behind vmcnt(0))
# speedup vs baseline: 1.0159x; 1.0102x over previous
.LBB0_268:
	s_cmpk_gt_i32 s10, 0x2ff
	s_cselect_b64 s[2:3], -1, 0
	s_add_i32 s0, s10, 0xfffffd00
	s_cmpk_lt_i32 s10, 0x300
	s_cselect_b32 s4, 24, 32
	v_cvt_f32_ubyte0_e32 v0, s4
	v_rcp_iflag_f32_e32 v0, v0
	s_movk_i32 s11, 0x180
	s_cselect_b32 s5, s10, s0
	s_cselect_b32 s0, 0, 0x300
	v_mul_f32_e32 v0, 0x4f7ffffe, v0
	v_cvt_u32_f32_e32 v0, v0
	s_cselect_b32 s13, s11, 0x80
	s_sub_i32 s14, 0, s4
	s_abs_i32 s12, s5
	v_readfirstlane_b32 s15, v0
	s_mul_i32 s14, s14, s15
	s_mul_hi_u32 s14, s15, s14
	s_add_i32 s15, s15, s14
	s_mul_hi_u32 s14, s12, s15
	s_mul_i32 s15, s14, s4
	s_sub_i32 s12, s12, s15
	s_ashr_i32 s11, s5, 31
	s_add_i32 s15, s14, 1
	s_sub_i32 s16, s12, s4
	s_cmp_ge_u32 s12, s4
	s_cselect_b32 s14, s15, s14
	s_cselect_b32 s12, s16, s12
	s_add_i32 s15, s14, 1
	s_cmp_ge_u32 s12, s4
	s_cselect_b32 s12, s15, s14
	s_xor_b32 s12, s12, s11
	s_sub_i32 s11, s12, s11
	s_mul_i32 s4, s11, s4
	s_sub_i32 s4, s5, s4
	s_bfe_i32 s5, s4, 0x80000
	s_bfe_u32 s5, s5, 0x2000d
	s_add_i32 s5, s4, s5
	s_bfe_i32 s12, s5, 0x80000
	s_and_b32 s5, s5, 0xfc
	s_sub_i32 s4, s4, s5
	s_sext_i32_i8 s4, s4
	s_lshl_b32 s5, s11, 10
	s_lshl_b32 s11, s4, 8
	s_add_i32 s11, s11, s5
	v_ashrrev_i32_e32 v2, 1, v42
	v_add_u32_e32 v4, s11, v2
	v_mov_b64_e32 v[0:1], s[88:89]
	v_mad_i64_i32 v[0:1], s[4:5], v4, s84, v[0:1]
	v_and_b32_e32 v3, 1, v42
	v_lshl_add_u64 v[0:1], v[0:1], 0, s[0:1]
	s_lshr_b32 s0, s13, 1
	v_mul_u32_u24_e32 v4, s0, v3
	s_sext_i32_i16 s12, s12
	v_lshlrev_b32_e32 v188, 1, v4
	s_lshr_b32 s12, s12, 2
	v_lshl_add_u64 v[0:1], v[0:1], 0, v[188:189]
	s_lshr_b32 s0, s13, 4
	v_mov_b32_e32 v4, 0
	global_load_dwordx4 v[12:15], v[0:1], off
	global_load_dwordx4 v[16:19], v[0:1], off offset:16
	global_load_dwordx4 v[20:23], v[0:1], off offset:32
	global_load_dwordx4 v[24:27], v[0:1], off offset:48
	global_load_dwordx4 v[28:31], v[0:1], off offset:64
	global_load_dwordx4 v[32:35], v[0:1], off offset:80
	global_load_dwordx4 v[36:39], v[0:1], off offset:96
	global_load_dwordx4 v[40:43], v[0:1], off offset:112
	s_cmp_lt_u32 s0, 9
	s_cbranch_scc1 .Lcst_ld8
	global_load_dwordx4 v[44:47], v[0:1], off offset:128
	global_load_dwordx4 v[48:51], v[0:1], off offset:144
	global_load_dwordx4 v[52:55], v[0:1], off offset:160
	global_load_dwordx4 v[56:59], v[0:1], off offset:176
	global_load_dwordx4 v[60:63], v[0:1], off offset:192
	global_load_dwordx4 v[64:67], v[0:1], off offset:208
	global_load_dwordx4 v[68:71], v[0:1], off offset:224
	global_load_dwordx4 v[72:75], v[0:1], off offset:240
	global_load_dwordx4 v[76:79], v[0:1], off offset:256
	global_load_dwordx4 v[80:83], v[0:1], off offset:272
	global_load_dwordx4 v[84:87], v[0:1], off offset:288
	global_load_dwordx4 v[88:91], v[0:1], off offset:304
	global_load_dwordx4 v[92:95], v[0:1], off offset:320
	global_load_dwordx4 v[96:99], v[0:1], off offset:336
	global_load_dwordx4 v[100:103], v[0:1], off offset:352
	global_load_dwordx4 v[104:107], v[0:1], off offset:368
.Lcst_ld8:
	s_waitcnt vmcnt(0)
	v_lshlrev_b32_e32 v5, 16, v12
	v_lshlrev_b32_e32 v11, 16, v13
	v_and_b32_e32 v10, 0xffff0000, v12
	v_fmac_f32_e32 v4, v5, v5
	v_pk_mul_f32 v[10:11], v[10:11], v[10:11]
	v_and_b32_e32 v5, 0xffff0000, v13
	v_add_f32_e32 v4, v10, v4
	v_add_f32_e32 v6, v11, v4
	v_lshlrev_b32_e32 v4, 16, v14
	v_pk_mul_f32 v[4:5], v[4:5], v[4:5]
	s_nop 0
	v_add_f32_e32 v5, v5, v6
	v_add_f32_e32 v6, v4, v5
	v_lshlrev_b32_e32 v5, 16, v15
	v_and_b32_e32 v4, 0xffff0000, v14
	v_pk_mul_f32 v[4:5], v[4:5], v[4:5]
	s_nop 0
	v_add_f32_e32 v4, v4, v6
	v_add_f32_e32 v4, v5, v4
	v_and_b32_e32 v5, 0xffff0000, v15
	v_fmac_f32_e32 v4, v5, v5
	v_lshlrev_b32_e32 v5, 16, v16
	v_lshlrev_b32_e32 v11, 16, v17
	v_and_b32_e32 v10, 0xffff0000, v16
	v_fmac_f32_e32 v4, v5, v5
	v_pk_mul_f32 v[10:11], v[10:11], v[10:11]
	v_and_b32_e32 v5, 0xffff0000, v17
	v_add_f32_e32 v4, v10, v4
	v_add_f32_e32 v6, v11, v4
	v_lshlrev_b32_e32 v4, 16, v18
	v_pk_mul_f32 v[4:5], v[4:5], v[4:5]
	s_nop 0
	v_add_f32_e32 v5, v5, v6
	v_add_f32_e32 v6, v4, v5
	v_lshlrev_b32_e32 v5, 16, v19
	v_and_b32_e32 v4, 0xffff0000, v18
	v_pk_mul_f32 v[4:5], v[4:5], v[4:5]
	s_nop 0
	v_add_f32_e32 v4, v4, v6
	v_add_f32_e32 v4, v5, v4
	v_and_b32_e32 v5, 0xffff0000, v19
	v_fmac_f32_e32 v4, v5, v5
	v_lshlrev_b32_e32 v5, 16, v20
	v_lshlrev_b32_e32 v11, 16, v21
	v_and_b32_e32 v10, 0xffff0000, v20
	v_fmac_f32_e32 v4, v5, v5
	v_pk_mul_f32 v[10:11], v[10:11], v[10:11]
	v_and_b32_e32 v5, 0xffff0000, v21
	v_add_f32_e32 v4, v10, v4
	v_add_f32_e32 v6, v11, v4
	v_lshlrev_b32_e32 v4, 16, v22
	v_pk_mul_f32 v[4:5], v[4:5], v[4:5]
	s_nop 0
	v_add_f32_e32 v5, v5, v6
	v_add_f32_e32 v6, v4, v5
	v_lshlrev_b32_e32 v5, 16, v23
	v_and_b32_e32 v4, 0xffff0000, v22
	v_pk_mul_f32 v[4:5], v[4:5], v[4:5]
	s_nop 0
	v_add_f32_e32 v4, v4, v6
	v_add_f32_e32 v4, v5, v4
	v_and_b32_e32 v5, 0xffff0000, v23
	v_fmac_f32_e32 v4, v5, v5
	v_lshlrev_b32_e32 v5, 16, v24
	v_lshlrev_b32_e32 v11, 16, v25
	v_and_b32_e32 v10, 0xffff0000, v24
	v_fmac_f32_e32 v4, v5, v5
	v_pk_mul_f32 v[10:11], v[10:11], v[10:11]
	v_and_b32_e32 v5, 0xffff0000, v25
	v_add_f32_e32 v4, v10, v4
	v_add_f32_e32 v6, v11, v4
	v_lshlrev_b32_e32 v4, 16, v26
	v_pk_mul_f32 v[4:5], v[4:5], v[4:5]
	s_nop 0
	v_add_f32_e32 v5, v5, v6
	v_add_f32_e32 v6, v4, v5
	v_lshlrev_b32_e32 v5, 16, v27
	v_and_b32_e32 v4, 0xffff0000, v26
	v_pk_mul_f32 v[4:5], v[4:5], v[4:5]
	s_nop 0
	v_add_f32_e32 v4, v4, v6
	v_add_f32_e32 v4, v5, v4
	v_and_b32_e32 v5, 0xffff0000, v27
	v_fmac_f32_e32 v4, v5, v5
	v_lshlrev_b32_e32 v5, 16, v28
	v_lshlrev_b32_e32 v11, 16, v29
	v_and_b32_e32 v10, 0xffff0000, v28
	v_fmac_f32_e32 v4, v5, v5
	v_pk_mul_f32 v[10:11], v[10:11], v[10:11]
	v_and_b32_e32 v5, 0xffff0000, v29
	v_add_f32_e32 v4, v10, v4
	v_add_f32_e32 v6, v11, v4
	v_lshlrev_b32_e32 v4, 16, v30
	v_pk_mul_f32 v[4:5], v[4:5], v[4:5]
	s_nop 0
	v_add_f32_e32 v5, v5, v6
	v_add_f32_e32 v6, v4, v5
	v_lshlrev_b32_e32 v5, 16, v31
	v_and_b32_e32 v4, 0xffff0000, v30
	v_pk_mul_f32 v[4:5], v[4:5], v[4:5]
	s_nop 0
	v_add_f32_e32 v4, v4, v6
	v_add_f32_e32 v4, v5, v4
	v_and_b32_e32 v5, 0xffff0000, v31
	v_fmac_f32_e32 v4, v5, v5
	v_lshlrev_b32_e32 v5, 16, v32
	v_lshlrev_b32_e32 v11, 16, v33
	v_and_b32_e32 v10, 0xffff0000, v32
	v_fmac_f32_e32 v4, v5, v5
	v_pk_mul_f32 v[10:11], v[10:11], v[10:11]
	v_and_b32_e32 v5, 0xffff0000, v33
	v_add_f32_e32 v4, v10, v4
	v_add_f32_e32 v6, v11, v4
	v_lshlrev_b32_e32 v4, 16, v34
	v_pk_mul_f32 v[4:5], v[4:5], v[4:5]
	s_nop 0
	v_add_f32_e32 v5, v5, v6
	v_add_f32_e32 v6, v4, v5
	v_lshlrev_b32_e32 v5, 16, v35
	v_and_b32_e32 v4, 0xffff0000, v34
	v_pk_mul_f32 v[4:5], v[4:5], v[4:5]
	s_nop 0
	v_add_f32_e32 v4, v4, v6
	v_add_f32_e32 v4, v5, v4
	v_and_b32_e32 v5, 0xffff0000, v35
	v_fmac_f32_e32 v4, v5, v5
	v_lshlrev_b32_e32 v5, 16, v36
	v_lshlrev_b32_e32 v11, 16, v37
	v_and_b32_e32 v10, 0xffff0000, v36
	v_fmac_f32_e32 v4, v5, v5
	v_pk_mul_f32 v[10:11], v[10:11], v[10:11]
	v_and_b32_e32 v5, 0xffff0000, v37
	v_add_f32_e32 v4, v10, v4
	v_add_f32_e32 v6, v11, v4
	v_lshlrev_b32_e32 v4, 16, v38
	v_pk_mul_f32 v[4:5], v[4:5], v[4:5]
	s_nop 0
	v_add_f32_e32 v5, v5, v6
	v_add_f32_e32 v6, v4, v5
	v_lshlrev_b32_e32 v5, 16, v39
	v_and_b32_e32 v4, 0xffff0000, v38
	v_pk_mul_f32 v[4:5], v[4:5], v[4:5]
	s_nop 0
	v_add_f32_e32 v4, v4, v6
	v_add_f32_e32 v4, v5, v4
	v_and_b32_e32 v5, 0xffff0000, v39
	v_fmac_f32_e32 v4, v5, v5
	v_lshlrev_b32_e32 v5, 16, v40
	v_lshlrev_b32_e32 v11, 16, v41
	v_and_b32_e32 v10, 0xffff0000, v40
	v_fmac_f32_e32 v4, v5, v5
	v_pk_mul_f32 v[10:11], v[10:11], v[10:11]
	v_and_b32_e32 v5, 0xffff0000, v41
	v_add_f32_e32 v4, v10, v4
	v_add_f32_e32 v6, v11, v4
	v_lshlrev_b32_e32 v4, 16, v42
	v_pk_mul_f32 v[4:5], v[4:5], v[4:5]
	s_nop 0
	v_add_f32_e32 v5, v5, v6
	v_add_f32_e32 v6, v4, v5
	v_lshlrev_b32_e32 v5, 16, v43
	v_and_b32_e32 v4, 0xffff0000, v42
	v_pk_mul_f32 v[4:5], v[4:5], v[4:5]
	s_nop 0
	v_add_f32_e32 v4, v4, v6
	v_add_f32_e32 v4, v5, v4
	v_and_b32_e32 v5, 0xffff0000, v43
	v_fmac_f32_e32 v4, v5, v5
	s_cmp_lt_u32 s0, 9
	s_cbranch_scc1 .Lcst_done
	v_lshlrev_b32_e32 v5, 16, v44
	v_lshlrev_b32_e32 v11, 16, v45
	v_and_b32_e32 v10, 0xffff0000, v44
	v_fmac_f32_e32 v4, v5, v5
	v_pk_mul_f32 v[10:11], v[10:11], v[10:11]
	v_and_b32_e32 v5, 0xffff0000, v45
	v_add_f32_e32 v4, v10, v4
	v_add_f32_e32 v6, v11, v4
	v_lshlrev_b32_e32 v4, 16, v46
	v_pk_mul_f32 v[4:5], v[4:5], v[4:5]
	s_nop 0
	v_add_f32_e32 v5, v5, v6
	v_add_f32_e32 v6, v4, v5
	v_lshlrev_b32_e32 v5, 16, v47
	v_and_b32_e32 v4, 0xffff0000, v46
	v_pk_mul_f32 v[4:5], v[4:5], v[4:5]
	s_nop 0
	v_add_f32_e32 v4, v4, v6
	v_add_f32_e32 v4, v5, v4
	v_and_b32_e32 v5, 0xffff0000, v47
	v_fmac_f32_e32 v4, v5, v5
	v_lshlrev_b32_e32 v5, 16, v48
	v_lshlrev_b32_e32 v11, 16, v49
	v_and_b32_e32 v10, 0xffff0000, v48
	v_fmac_f32_e32 v4, v5, v5
	v_pk_mul_f32 v[10:11], v[10:11], v[10:11]
	v_and_b32_e32 v5, 0xffff0000, v49
	v_add_f32_e32 v4, v10, v4
	v_add_f32_e32 v6, v11, v4
	v_lshlrev_b32_e32 v4, 16, v50
	v_pk_mul_f32 v[4:5], v[4:5], v[4:5]
	s_nop 0
	v_add_f32_e32 v5, v5, v6
	v_add_f32_e32 v6, v4, v5
	v_lshlrev_b32_e32 v5, 16, v51
	v_and_b32_e32 v4, 0xffff0000, v50
	v_pk_mul_f32 v[4:5], v[4:5], v[4:5]
	s_nop 0
	v_add_f32_e32 v4, v4, v6
	v_add_f32_e32 v4, v5, v4
	v_and_b32_e32 v5, 0xffff0000, v51
	v_fmac_f32_e32 v4, v5, v5
	v_lshlrev_b32_e32 v5, 16, v52
	v_lshlrev_b32_e32 v11, 16, v53
	v_and_b32_e32 v10, 0xffff0000, v52
	v_fmac_f32_e32 v4, v5, v5
	v_pk_mul_f32 v[10:11], v[10:11], v[10:11]
	v_and_b32_e32 v5, 0xffff0000, v53
	v_add_f32_e32 v4, v10, v4
	v_add_f32_e32 v6, v11, v4
	v_lshlrev_b32_e32 v4, 16, v54
	v_pk_mul_f32 v[4:5], v[4:5], v[4:5]
	s_nop 0
	v_add_f32_e32 v5, v5, v6
	v_add_f32_e32 v6, v4, v5
	v_lshlrev_b32_e32 v5, 16, v55
	v_and_b32_e32 v4, 0xffff0000, v54
	v_pk_mul_f32 v[4:5], v[4:5], v[4:5]
	s_nop 0
	v_add_f32_e32 v4, v4, v6
	v_add_f32_e32 v4, v5, v4
	v_and_b32_e32 v5, 0xffff0000, v55
	v_fmac_f32_e32 v4, v5, v5
	v_lshlrev_b32_e32 v5, 16, v56
	v_lshlrev_b32_e32 v11, 16, v57
	v_and_b32_e32 v10, 0xffff0000, v56
	v_fmac_f32_e32 v4, v5, v5
	v_pk_mul_f32 v[10:11], v[10:11], v[10:11]
	v_and_b32_e32 v5, 0xffff0000, v57
	v_add_f32_e32 v4, v10, v4
	v_add_f32_e32 v6, v11, v4
	v_lshlrev_b32_e32 v4, 16, v58
	v_pk_mul_f32 v[4:5], v[4:5], v[4:5]
	s_nop 0
	v_add_f32_e32 v5, v5, v6
	v_add_f32_e32 v6, v4, v5
	v_lshlrev_b32_e32 v5, 16, v59
	v_and_b32_e32 v4, 0xffff0000, v58
	v_pk_mul_f32 v[4:5], v[4:5], v[4:5]
	s_nop 0
	v_add_f32_e32 v4, v4, v6
	v_add_f32_e32 v4, v5, v4
	v_and_b32_e32 v5, 0xffff0000, v59
	v_fmac_f32_e32 v4, v5, v5
	v_lshlrev_b32_e32 v5, 16, v60
	v_lshlrev_b32_e32 v11, 16, v61
	v_and_b32_e32 v10, 0xffff0000, v60
	v_fmac_f32_e32 v4, v5, v5
	v_pk_mul_f32 v[10:11], v[10:11], v[10:11]
	v_and_b32_e32 v5, 0xffff0000, v61
	v_add_f32_e32 v4, v10, v4
	v_add_f32_e32 v6, v11, v4
	v_lshlrev_b32_e32 v4, 16, v62
	v_pk_mul_f32 v[4:5], v[4:5], v[4:5]
	s_nop 0
	v_add_f32_e32 v5, v5, v6
	v_add_f32_e32 v6, v4, v5
	v_lshlrev_b32_e32 v5, 16, v63
	v_and_b32_e32 v4, 0xffff0000, v62
	v_pk_mul_f32 v[4:5], v[4:5], v[4:5]
	s_nop 0
	v_add_f32_e32 v4, v4, v6
	v_add_f32_e32 v4, v5, v4
	v_and_b32_e32 v5, 0xffff0000, v63
	v_fmac_f32_e32 v4, v5, v5
	v_lshlrev_b32_e32 v5, 16, v64
	v_lshlrev_b32_e32 v11, 16, v65
	v_and_b32_e32 v10, 0xffff0000, v64
	v_fmac_f32_e32 v4, v5, v5
	v_pk_mul_f32 v[10:11], v[10:11], v[10:11]
	v_and_b32_e32 v5, 0xffff0000, v65
	v_add_f32_e32 v4, v10, v4
	v_add_f32_e32 v6, v11, v4
	v_lshlrev_b32_e32 v4, 16, v66
	v_pk_mul_f32 v[4:5], v[4:5], v[4:5]
	s_nop 0
	v_add_f32_e32 v5, v5, v6
	v_add_f32_e32 v6, v4, v5
	v_lshlrev_b32_e32 v5, 16, v67
	v_and_b32_e32 v4, 0xffff0000, v66
	v_pk_mul_f32 v[4:5], v[4:5], v[4:5]
	s_nop 0
	v_add_f32_e32 v4, v4, v6
	v_add_f32_e32 v4, v5, v4
	v_and_b32_e32 v5, 0xffff0000, v67
	v_fmac_f32_e32 v4, v5, v5
	v_lshlrev_b32_e32 v5, 16, v68
	v_lshlrev_b32_e32 v11, 16, v69
	v_and_b32_e32 v10, 0xffff0000, v68
	v_fmac_f32_e32 v4, v5, v5
	v_pk_mul_f32 v[10:11], v[10:11], v[10:11]
	v_and_b32_e32 v5, 0xffff0000, v69
	v_add_f32_e32 v4, v10, v4
	v_add_f32_e32 v6, v11, v4
	v_lshlrev_b32_e32 v4, 16, v70
	v_pk_mul_f32 v[4:5], v[4:5], v[4:5]
	s_nop 0
	v_add_f32_e32 v5, v5, v6
	v_add_f32_e32 v6, v4, v5
	v_lshlrev_b32_e32 v5, 16, v71
	v_and_b32_e32 v4, 0xffff0000, v70
	v_pk_mul_f32 v[4:5], v[4:5], v[4:5]
	s_nop 0
	v_add_f32_e32 v4, v4, v6
	v_add_f32_e32 v4, v5, v4
	v_and_b32_e32 v5, 0xffff0000, v71
	v_fmac_f32_e32 v4, v5, v5
	v_lshlrev_b32_e32 v5, 16, v72
	v_lshlrev_b32_e32 v11, 16, v73
	v_and_b32_e32 v10, 0xffff0000, v72
	v_fmac_f32_e32 v4, v5, v5
	v_pk_mul_f32 v[10:11], v[10:11], v[10:11]
	v_and_b32_e32 v5, 0xffff0000, v73
	v_add_f32_e32 v4, v10, v4
	v_add_f32_e32 v6, v11, v4
	v_lshlrev_b32_e32 v4, 16, v74
	v_pk_mul_f32 v[4:5], v[4:5], v[4:5]
	s_nop 0
	v_add_f32_e32 v5, v5, v6
	v_add_f32_e32 v6, v4, v5
	v_lshlrev_b32_e32 v5, 16, v75
	v_and_b32_e32 v4, 0xffff0000, v74
	v_pk_mul_f32 v[4:5], v[4:5], v[4:5]
	s_nop 0
	v_add_f32_e32 v4, v4, v6
	v_add_f32_e32 v4, v5, v4
	v_and_b32_e32 v5, 0xffff0000, v75
	v_fmac_f32_e32 v4, v5, v5
	v_lshlrev_b32_e32 v5, 16, v76
	v_lshlrev_b32_e32 v11, 16, v77
	v_and_b32_e32 v10, 0xffff0000, v76
	v_fmac_f32_e32 v4, v5, v5
	v_pk_mul_f32 v[10:11], v[10:11], v[10:11]
	v_and_b32_e32 v5, 0xffff0000, v77
	v_add_f32_e32 v4, v10, v4
	v_add_f32_e32 v6, v11, v4
	v_lshlrev_b32_e32 v4, 16, v78
	v_pk_mul_f32 v[4:5], v[4:5], v[4:5]
	s_nop 0
	v_add_f32_e32 v5, v5, v6
	v_add_f32_e32 v6, v4, v5
	v_lshlrev_b32_e32 v5, 16, v79
	v_and_b32_e32 v4, 0xffff0000, v78
	v_pk_mul_f32 v[4:5], v[4:5], v[4:5]
	s_nop 0
	v_add_f32_e32 v4, v4, v6
	v_add_f32_e32 v4, v5, v4
	v_and_b32_e32 v5, 0xffff0000, v79
	v_fmac_f32_e32 v4, v5, v5
	v_lshlrev_b32_e32 v5, 16, v80
	v_lshlrev_b32_e32 v11, 16, v81
	v_and_b32_e32 v10, 0xffff0000, v80
	v_fmac_f32_e32 v4, v5, v5
	v_pk_mul_f32 v[10:11], v[10:11], v[10:11]
	v_and_b32_e32 v5, 0xffff0000, v81
	v_add_f32_e32 v4, v10, v4
	v_add_f32_e32 v6, v11, v4
	v_lshlrev_b32_e32 v4, 16, v82
	v_pk_mul_f32 v[4:5], v[4:5], v[4:5]
	s_nop 0
	v_add_f32_e32 v5, v5, v6
	v_add_f32_e32 v6, v4, v5
	v_lshlrev_b32_e32 v5, 16, v83
	v_and_b32_e32 v4, 0xffff0000, v82
	v_pk_mul_f32 v[4:5], v[4:5], v[4:5]
	s_nop 0
	v_add_f32_e32 v4, v4, v6
	v_add_f32_e32 v4, v5, v4
	v_and_b32_e32 v5, 0xffff0000, v83
	v_fmac_f32_e32 v4, v5, v5
	v_lshlrev_b32_e32 v5, 16, v84
	v_lshlrev_b32_e32 v11, 16, v85
	v_and_b32_e32 v10, 0xffff0000, v84
	v_fmac_f32_e32 v4, v5, v5
	v_pk_mul_f32 v[10:11], v[10:11], v[10:11]
	v_and_b32_e32 v5, 0xffff0000, v85
	v_add_f32_e32 v4, v10, v4
	v_add_f32_e32 v6, v11, v4
	v_lshlrev_b32_e32 v4, 16, v86
	v_pk_mul_f32 v[4:5], v[4:5], v[4:5]
	s_nop 0
	v_add_f32_e32 v5, v5, v6
	v_add_f32_e32 v6, v4, v5
	v_lshlrev_b32_e32 v5, 16, v87
	v_and_b32_e32 v4, 0xffff0000, v86
	v_pk_mul_f32 v[4:5], v[4:5], v[4:5]
	s_nop 0
	v_add_f32_e32 v4, v4, v6
	v_add_f32_e32 v4, v5, v4
	v_and_b32_e32 v5, 0xffff0000, v87
	v_fmac_f32_e32 v4, v5, v5
	v_lshlrev_b32_e32 v5, 16, v88
	v_lshlrev_b32_e32 v11, 16, v89
	v_and_b32_e32 v10, 0xffff0000, v88
	v_fmac_f32_e32 v4, v5, v5
	v_pk_mul_f32 v[10:11], v[10:11], v[10:11]
	v_and_b32_e32 v5, 0xffff0000, v89
	v_add_f32_e32 v4, v10, v4
	v_add_f32_e32 v6, v11, v4
	v_lshlrev_b32_e32 v4, 16, v90
	v_pk_mul_f32 v[4:5], v[4:5], v[4:5]
	s_nop 0
	v_add_f32_e32 v5, v5, v6
	v_add_f32_e32 v6, v4, v5
	v_lshlrev_b32_e32 v5, 16, v91
	v_and_b32_e32 v4, 0xffff0000, v90
	v_pk_mul_f32 v[4:5], v[4:5], v[4:5]
	s_nop 0
	v_add_f32_e32 v4, v4, v6
	v_add_f32_e32 v4, v5, v4
	v_and_b32_e32 v5, 0xffff0000, v91
	v_fmac_f32_e32 v4, v5, v5
	v_lshlrev_b32_e32 v5, 16, v92
	v_lshlrev_b32_e32 v11, 16, v93
	v_and_b32_e32 v10, 0xffff0000, v92
	v_fmac_f32_e32 v4, v5, v5
	v_pk_mul_f32 v[10:11], v[10:11], v[10:11]
	v_and_b32_e32 v5, 0xffff0000, v93
	v_add_f32_e32 v4, v10, v4
	v_add_f32_e32 v6, v11, v4
	v_lshlrev_b32_e32 v4, 16, v94
	v_pk_mul_f32 v[4:5], v[4:5], v[4:5]
	s_nop 0
	v_add_f32_e32 v5, v5, v6
	v_add_f32_e32 v6, v4, v5
	v_lshlrev_b32_e32 v5, 16, v95
	v_and_b32_e32 v4, 0xffff0000, v94
	v_pk_mul_f32 v[4:5], v[4:5], v[4:5]
	s_nop 0
	v_add_f32_e32 v4, v4, v6
	v_add_f32_e32 v4, v5, v4
	v_and_b32_e32 v5, 0xffff0000, v95
	v_fmac_f32_e32 v4, v5, v5
	v_lshlrev_b32_e32 v5, 16, v96
	v_lshlrev_b32_e32 v11, 16, v97
	v_and_b32_e32 v10, 0xffff0000, v96
	v_fmac_f32_e32 v4, v5, v5
	v_pk_mul_f32 v[10:11], v[10:11], v[10:11]
	v_and_b32_e32 v5, 0xffff0000, v97
	v_add_f32_e32 v4, v10, v4
	v_add_f32_e32 v6, v11, v4
	v_lshlrev_b32_e32 v4, 16, v98
	v_pk_mul_f32 v[4:5], v[4:5], v[4:5]
	s_nop 0
	v_add_f32_e32 v5, v5, v6
	v_add_f32_e32 v6, v4, v5
	v_lshlrev_b32_e32 v5, 16, v99
	v_and_b32_e32 v4, 0xffff0000, v98
	v_pk_mul_f32 v[4:5], v[4:5], v[4:5]
	s_nop 0
	v_add_f32_e32 v4, v4, v6
	v_add_f32_e32 v4, v5, v4
	v_and_b32_e32 v5, 0xffff0000, v99
	v_fmac_f32_e32 v4, v5, v5
	v_lshlrev_b32_e32 v5, 16, v100
	v_lshlrev_b32_e32 v11, 16, v101
	v_and_b32_e32 v10, 0xffff0000, v100
	v_fmac_f32_e32 v4, v5, v5
	v_pk_mul_f32 v[10:11], v[10:11], v[10:11]
	v_and_b32_e32 v5, 0xffff0000, v101
	v_add_f32_e32 v4, v10, v4
	v_add_f32_e32 v6, v11, v4
	v_lshlrev_b32_e32 v4, 16, v102
	v_pk_mul_f32 v[4:5], v[4:5], v[4:5]
	s_nop 0
	v_add_f32_e32 v5, v5, v6
	v_add_f32_e32 v6, v4, v5
	v_lshlrev_b32_e32 v5, 16, v103
	v_and_b32_e32 v4, 0xffff0000, v102
	v_pk_mul_f32 v[4:5], v[4:5], v[4:5]
	s_nop 0
	v_add_f32_e32 v4, v4, v6
	v_add_f32_e32 v4, v5, v4
	v_and_b32_e32 v5, 0xffff0000, v103
	v_fmac_f32_e32 v4, v5, v5
	v_lshlrev_b32_e32 v5, 16, v104
	v_lshlrev_b32_e32 v11, 16, v105
	v_and_b32_e32 v10, 0xffff0000, v104
	v_fmac_f32_e32 v4, v5, v5
	v_pk_mul_f32 v[10:11], v[10:11], v[10:11]
	v_and_b32_e32 v5, 0xffff0000, v105
	v_add_f32_e32 v4, v10, v4
	v_add_f32_e32 v6, v11, v4
	v_lshlrev_b32_e32 v4, 16, v106
	v_pk_mul_f32 v[4:5], v[4:5], v[4:5]
	s_nop 0
	v_add_f32_e32 v5, v5, v6
	v_add_f32_e32 v6, v4, v5
	v_lshlrev_b32_e32 v5, 16, v107
	v_and_b32_e32 v4, 0xffff0000, v106
	v_pk_mul_f32 v[4:5], v[4:5], v[4:5]
	s_nop 0
	v_add_f32_e32 v4, v4, v6
	v_add_f32_e32 v4, v5, v4
	v_and_b32_e32 v5, 0xffff0000, v107
	v_fmac_f32_e32 v4, v5, v5
.Lcst_done:
	v_and_b32_e32 v1, 64, v207
	v_xor_b32_e32 v0, 1, v207
	v_add_u32_e32 v1, 64, v1
	v_cmp_lt_i32_e32 vcc, v0, v1
	s_nop 1
	v_cndmask_b32_e32 v0, v207, v0, vcc
	v_lshlrev_b32_e32 v0, 2, v0
	ds_bpermute_b32 v0, v0, v4
	v_cmp_eq_u32_e32 vcc, 0, v3
	s_and_saveexec_b64 s[4:5], vcc
	s_cbranch_execz .LBB0_272
	v_cvt_f32_u32_e32 v1, s13
	s_waitcnt lgkmcnt(0)
	v_add_f32_e32 v0, v4, v0
	v_div_scale_f32 v3, s[14:15], v1, v1, v0
	v_rcp_f32_e32 v4, v3
	v_div_scale_f32 v5, vcc, v0, v1, v0
	v_fma_f32 v6, -v3, v4, 1.0
	v_fmac_f32_e32 v4, v6, v4
	v_mul_f32_e32 v6, v5, v4
	v_fma_f32 v7, -v3, v6, v5
	v_fmac_f32_e32 v6, v7, v4
	v_fma_f32 v3, -v3, v6, v5
	v_div_fmas_f32 v3, v3, v4, v6
	v_div_fixup_f32 v0, v3, v1, v0
	v_add_f32_e32 v0, 0x358637bd, v0
	v_mul_f32_e32 v1, 0x4b800000, v0
	v_cmp_gt_f32_e32 vcc, s30, v0
	s_nop 1
	v_cndmask_b32_e32 v0, v0, v1, vcc
	v_rsq_f32_e32 v0, v0
	v_lshl_add_u32 v1, v2, 2, 0
	v_add_u32_e32 v1, 0x24000, v1
	v_mul_f32_e32 v2, 0x45800000, v0
	v_cndmask_b32_e32 v0, v0, v2, vcc
	ds_write_b32 v1, v0
